# adds hand-written pipelined final-layer down-projection epilogue (EpiFinal both halves)
# baseline (speedup 1.0000x reference)
;     __device__ __forceinline__ void operator()(f32x4 (&acc)[2][2][4][2], const Unit& u, int wr, int wc, int fr, int fq) const {
;     ...
;                 for (int bj = 0; bj < 2; ++bj) { const f32x4* hi = (const f32x4*)(Hin + (size_t)row * 1024 + col0 + bj * HALF);
;                     const f32x4 v0 = acc[ai][bj][m][0] + hi[0], v1 = acc[ai][bj][m][1] + hi[1]; acc[ai][bj][m][0] = v0; acc[ai][bj][m][1] = v1;
;                     ss += ((v0[0] * v0[0] + v0[1] * v0[1]) + (v0[2] * v0[2] + v0[3] * v0[3])) + ((v1[0] * v1[0] + v1[1] * v1[1]) + (v1[2] * v1[2] + v1[3] * v1[3])); }
;                 ss += __shfl_xor(ss, 16); ss += __shfl_xor(ss, 32);
;                 if (fq == 0) __hip_atomic_store(part + (size_t)row * 16 + u.pn * 4 + wc, ss, __ATOMIC_RELAXED, __HIP_MEMORY_SCOPE_AGENT);
;             }
.LBB0_1742:
	s_mov_b32 s32, s22
	s_mov_b32 s51, s23
	v_lshlrev_b32_e32 v170, 12, v184
	v_lshl_add_u32 v170, v195, 2, v170
	v_lshlrev_b32_e32 v176, 6, v184
	v_xor_b32_e32 v177, 16, v221
	v_lshlrev_b32_e32 v177, 2, v177
	s_lshl_b32 s65, s32, 20
	s_add_u32 s98, s54, s65
	s_addc_u32 s99, s55, 0
	s_lshl_b32 s65, s51, 10
	s_add_u32 s98, s98, s65
	s_addc_u32 s99, s99, 0
	s_lshl_b32 s65, s32, 14
	s_add_u32 s60, s10, s65
	s_addc_u32 s61, s11, 0
	s_lshl_b32 s65, s51, 2
	s_add_i32 s65, s65, s9
	s_lshl_b32 s65, s65, 2
	s_add_u32 s60, s60, s65
	s_addc_u32 s61, s61, 0
	global_load_dwordx4 v[142:145], v170, s[98:99]
	global_load_dwordx4 v[146:149], v170, s[98:99] offset:16
	global_load_dwordx4 v[150:153], v170, s[98:99] offset:512
	global_load_dwordx4 v[154:157], v170, s[98:99] offset:528
	s_add_u32 s98, s98, 0x10000
	s_addc_u32 s99, s99, 0
	global_load_dwordx4 v[158:161], v170, s[98:99]
	global_load_dwordx4 v[162:165], v170, s[98:99] offset:16
	global_load_dwordx4 v[166:169], v170, s[98:99] offset:512
	global_load_dwordx4 v[186:189], v170, s[98:99] offset:528
	s_add_u32 s98, s98, 0x10000
	s_addc_u32 s99, s99, 0
	global_load_dwordx4 v[190:193], v170, s[98:99]
	global_load_dwordx4 v[198:201], v170, s[98:99] offset:16
	global_load_dwordx4 v[202:205], v170, s[98:99] offset:512
	global_load_dwordx4 v[210:213], v170, s[98:99] offset:528
	s_add_u32 s98, s98, 0x10000
	s_addc_u32 s99, s99, 0
	global_load_dwordx4 v[234:237], v170, s[98:99]
	global_load_dwordx4 v[238:241], v170, s[98:99] offset:16
	global_load_dwordx4 v[242:245], v170, s[98:99] offset:512
	global_load_dwordx4 v[246:249], v170, s[98:99] offset:528
	s_waitcnt vmcnt(12)
	v_pk_add_f32 v[126:127], v[126:127], v[142:143]
	v_pk_add_f32 v[128:129], v[128:129], v[144:145]
	v_pk_add_f32 v[122:123], v[122:123], v[146:147]
	v_pk_add_f32 v[124:125], v[124:125], v[148:149]
	v_pk_add_f32 v[118:119], v[118:119], v[150:151]
	v_pk_add_f32 v[120:121], v[120:121], v[152:153]
	v_pk_add_f32 v[114:115], v[114:115], v[154:155]
	v_pk_add_f32 v[116:117], v[116:117], v[156:157]
	s_add_u32 s98, s98, 0x50000
	s_addc_u32 s99, s99, 0
	global_load_dwordx4 v[142:145], v170, s[98:99]
	global_load_dwordx4 v[146:149], v170, s[98:99] offset:16
	global_load_dwordx4 v[150:153], v170, s[98:99] offset:512
	global_load_dwordx4 v[154:157], v170, s[98:99] offset:528
	v_mul_f32_e32 v233, v126, v126
	v_mul_f32_e32 v250, v122, v122
	v_fmac_f32_e32 v233, v127, v127
	v_fmac_f32_e32 v233, v128, v128
	v_fmac_f32_e32 v233, v129, v129
	v_fmac_f32_e32 v250, v123, v123
	v_fmac_f32_e32 v250, v124, v124
	v_fmac_f32_e32 v250, v125, v125
	v_fmac_f32_e32 v233, v118, v118
	v_fmac_f32_e32 v233, v119, v119
	v_fmac_f32_e32 v233, v120, v120
	v_fmac_f32_e32 v233, v121, v121
	v_fmac_f32_e32 v250, v114, v114
	v_fmac_f32_e32 v250, v115, v115
	v_fmac_f32_e32 v250, v116, v116
	v_fmac_f32_e32 v250, v117, v117
	v_add_f32_e32 v233, v233, v250
	ds_bpermute_b32 v250, v177, v233
	s_waitcnt lgkmcnt(0)
	v_add_f32_e32 v233, v233, v250
	v_mov_b32_e32 v250, v233
	s_nop 1
	v_permlane32_swap_b32_e32 v250, v233
	v_add_f32_e32 v251, v233, v250
	s_and_saveexec_b64 s[62:63], s[42:43]
	global_store_dword v176, v251, s[60:61] sc1
	s_or_b64 exec, exec, s[62:63]
	s_add_u32 s60, s60, 0x400
	s_addc_u32 s61, s61, 0
	s_waitcnt vmcnt(13)
	v_pk_add_f32 v[110:111], v[110:111], v[158:159]
	v_pk_add_f32 v[112:113], v[112:113], v[160:161]
	v_pk_add_f32 v[106:107], v[106:107], v[162:163]
	v_pk_add_f32 v[108:109], v[108:109], v[164:165]
	v_pk_add_f32 v[102:103], v[102:103], v[166:167]
	v_pk_add_f32 v[104:105], v[104:105], v[168:169]
	v_pk_add_f32 v[98:99], v[98:99], v[186:187]
	v_pk_add_f32 v[100:101], v[100:101], v[188:189]
	s_add_u32 s98, s98, 0x10000
	s_addc_u32 s99, s99, 0
	global_load_dwordx4 v[158:161], v170, s[98:99]
	global_load_dwordx4 v[162:165], v170, s[98:99] offset:16
	global_load_dwordx4 v[166:169], v170, s[98:99] offset:512
	global_load_dwordx4 v[186:189], v170, s[98:99] offset:528
	v_mul_f32_e32 v233, v110, v110
	v_mul_f32_e32 v250, v106, v106
	v_fmac_f32_e32 v233, v111, v111
	v_fmac_f32_e32 v233, v112, v112
	v_fmac_f32_e32 v233, v113, v113
	v_fmac_f32_e32 v250, v107, v107
	v_fmac_f32_e32 v250, v108, v108
	v_fmac_f32_e32 v250, v109, v109
	v_fmac_f32_e32 v233, v102, v102
	v_fmac_f32_e32 v233, v103, v103
	v_fmac_f32_e32 v233, v104, v104
	v_fmac_f32_e32 v233, v105, v105
	v_fmac_f32_e32 v250, v98, v98
	v_fmac_f32_e32 v250, v99, v99
	v_fmac_f32_e32 v250, v100, v100
	v_fmac_f32_e32 v250, v101, v101
	v_add_f32_e32 v233, v233, v250
	ds_bpermute_b32 v250, v177, v233
	s_waitcnt lgkmcnt(0)
	v_add_f32_e32 v233, v233, v250
	v_mov_b32_e32 v250, v233
	s_nop 1
	v_permlane32_swap_b32_e32 v250, v233
	v_add_f32_e32 v251, v233, v250
	s_and_saveexec_b64 s[62:63], s[42:43]
	global_store_dword v176, v251, s[60:61] sc1
	s_or_b64 exec, exec, s[62:63]
	s_add_u32 s60, s60, 0x400
	s_addc_u32 s61, s61, 0
	s_waitcnt vmcnt(14)
	v_pk_add_f32 v[94:95], v[94:95], v[190:191]
	v_pk_add_f32 v[96:97], v[96:97], v[192:193]
	v_pk_add_f32 v[90:91], v[90:91], v[198:199]
	v_pk_add_f32 v[92:93], v[92:93], v[200:201]
	v_pk_add_f32 v[86:87], v[86:87], v[202:203]
	v_pk_add_f32 v[88:89], v[88:89], v[204:205]
	v_pk_add_f32 v[82:83], v[82:83], v[210:211]
	v_pk_add_f32 v[84:85], v[84:85], v[212:213]
	s_add_u32 s98, s98, 0x10000
	s_addc_u32 s99, s99, 0
	global_load_dwordx4 v[190:193], v170, s[98:99]
	global_load_dwordx4 v[198:201], v170, s[98:99] offset:16
	global_load_dwordx4 v[202:205], v170, s[98:99] offset:512
	global_load_dwordx4 v[210:213], v170, s[98:99] offset:528
	v_mul_f32_e32 v233, v94, v94
	v_mul_f32_e32 v250, v90, v90
	v_fmac_f32_e32 v233, v95, v95
	v_fmac_f32_e32 v233, v96, v96
	v_fmac_f32_e32 v233, v97, v97
	v_fmac_f32_e32 v250, v91, v91
	v_fmac_f32_e32 v250, v92, v92
	v_fmac_f32_e32 v250, v93, v93
	v_fmac_f32_e32 v233, v86, v86
	v_fmac_f32_e32 v233, v87, v87
	v_fmac_f32_e32 v233, v88, v88
	v_fmac_f32_e32 v233, v89, v89
	v_fmac_f32_e32 v250, v82, v82
	v_fmac_f32_e32 v250, v83, v83
	v_fmac_f32_e32 v250, v84, v84
	v_fmac_f32_e32 v250, v85, v85
	v_add_f32_e32 v233, v233, v250
	ds_bpermute_b32 v250, v177, v233
	s_waitcnt lgkmcnt(0)
;     __device__ __forceinline__ void operator()(f32x4 (&acc)[2][2][4][2], const Unit& u, int wr, int wc, int fr, int fq) const {
;     ...
;                 for (int bj = 0; bj < 2; ++bj) { const f32x4* hi = (const f32x4*)(Hin + (size_t)row * 1024 + col0 + bj * HALF);
;                     const f32x4 v0 = acc[ai][bj][m][0] + hi[0], v1 = acc[ai][bj][m][1] + hi[1]; acc[ai][bj][m][0] = v0; acc[ai][bj][m][1] = v1;
;                     ss += ((v0[0] * v0[0] + v0[1] * v0[1]) + (v0[2] * v0[2] + v0[3] * v0[3])) + ((v1[0] * v1[0] + v1[1] * v1[1]) + (v1[2] * v1[2] + v1[3] * v1[3])); }
;                 ss += __shfl_xor(ss, 16); ss += __shfl_xor(ss, 32);
;                 if (fq == 0) __hip_atomic_store(part + (size_t)row * 16 + u.pn * 4 + wc, ss, __ATOMIC_RELAXED, __HIP_MEMORY_SCOPE_AGENT);
;             }
	v_add_f32_e32 v233, v233, v250
	v_mov_b32_e32 v250, v233
	s_nop 1
	v_permlane32_swap_b32_e32 v250, v233
	v_add_f32_e32 v251, v233, v250
	s_and_saveexec_b64 s[62:63], s[42:43]
	global_store_dword v176, v251, s[60:61] sc1
	s_or_b64 exec, exec, s[62:63]
	s_add_u32 s60, s60, 0x400
	s_addc_u32 s61, s61, 0
	s_waitcnt vmcnt(15)
	v_pk_add_f32 v[78:79], v[78:79], v[234:235]
	v_pk_add_f32 v[80:81], v[80:81], v[236:237]
	v_pk_add_f32 v[74:75], v[74:75], v[238:239]
	v_pk_add_f32 v[76:77], v[76:77], v[240:241]
	v_pk_add_f32 v[70:71], v[70:71], v[242:243]
	v_pk_add_f32 v[72:73], v[72:73], v[244:245]
	v_pk_add_f32 v[66:67], v[66:67], v[246:247]
	v_pk_add_f32 v[68:69], v[68:69], v[248:249]
	s_add_u32 s98, s98, 0x10000
	s_addc_u32 s99, s99, 0
	global_load_dwordx4 v[234:237], v170, s[98:99]
	global_load_dwordx4 v[238:241], v170, s[98:99] offset:16
	global_load_dwordx4 v[242:245], v170, s[98:99] offset:512
	global_load_dwordx4 v[246:249], v170, s[98:99] offset:528
	v_mul_f32_e32 v233, v78, v78
	v_mul_f32_e32 v250, v74, v74
	v_fmac_f32_e32 v233, v79, v79
	v_fmac_f32_e32 v233, v80, v80
	v_fmac_f32_e32 v233, v81, v81
	v_fmac_f32_e32 v250, v75, v75
	v_fmac_f32_e32 v250, v76, v76
	v_fmac_f32_e32 v250, v77, v77
	v_fmac_f32_e32 v233, v70, v70
	v_fmac_f32_e32 v233, v71, v71
	v_fmac_f32_e32 v233, v72, v72
	v_fmac_f32_e32 v233, v73, v73
	v_fmac_f32_e32 v250, v66, v66
	v_fmac_f32_e32 v250, v67, v67
	v_fmac_f32_e32 v250, v68, v68
	v_fmac_f32_e32 v250, v69, v69
	v_add_f32_e32 v233, v233, v250
	ds_bpermute_b32 v250, v177, v233
	s_waitcnt lgkmcnt(0)
	v_add_f32_e32 v233, v233, v250
	v_mov_b32_e32 v250, v233
	s_nop 1
	v_permlane32_swap_b32_e32 v250, v233
	v_add_f32_e32 v251, v233, v250
	s_and_saveexec_b64 s[62:63], s[42:43]
	global_store_dword v176, v251, s[60:61] sc1
	s_or_b64 exec, exec, s[62:63]
	s_add_u32 s60, s60, 0x1400
	s_addc_u32 s61, s61, 0
	s_waitcnt vmcnt(16)
	v_pk_add_f32 v[62:63], v[62:63], v[142:143]
	v_pk_add_f32 v[64:65], v[64:65], v[144:145]
	v_pk_add_f32 v[58:59], v[58:59], v[146:147]
	v_pk_add_f32 v[60:61], v[60:61], v[148:149]
	v_pk_add_f32 v[54:55], v[54:55], v[150:151]
	v_pk_add_f32 v[56:57], v[56:57], v[152:153]
	v_pk_add_f32 v[50:51], v[50:51], v[154:155]
	v_pk_add_f32 v[52:53], v[52:53], v[156:157]
	v_mul_f32_e32 v233, v62, v62
	v_mul_f32_e32 v250, v58, v58
	v_fmac_f32_e32 v233, v63, v63
	v_fmac_f32_e32 v233, v64, v64
	v_fmac_f32_e32 v233, v65, v65
	v_fmac_f32_e32 v250, v59, v59
	v_fmac_f32_e32 v250, v60, v60
	v_fmac_f32_e32 v250, v61, v61
	v_fmac_f32_e32 v233, v54, v54
	v_fmac_f32_e32 v233, v55, v55
	v_fmac_f32_e32 v233, v56, v56
	v_fmac_f32_e32 v233, v57, v57
	v_fmac_f32_e32 v250, v50, v50
	v_fmac_f32_e32 v250, v51, v51
	v_fmac_f32_e32 v250, v52, v52
	v_fmac_f32_e32 v250, v53, v53
	v_add_f32_e32 v233, v233, v250
	ds_bpermute_b32 v250, v177, v233
	s_waitcnt lgkmcnt(0)
	v_add_f32_e32 v233, v233, v250
	v_mov_b32_e32 v250, v233
	s_nop 1
	v_permlane32_swap_b32_e32 v250, v233
	v_add_f32_e32 v251, v233, v250
	s_and_saveexec_b64 s[62:63], s[42:43]
	global_store_dword v176, v251, s[60:61] sc1
	s_or_b64 exec, exec, s[62:63]
	s_add_u32 s60, s60, 0x400
	s_addc_u32 s61, s61, 0
	s_waitcnt vmcnt(12)
	v_pk_add_f32 v[46:47], v[46:47], v[158:159]
	v_pk_add_f32 v[48:49], v[48:49], v[160:161]
	v_pk_add_f32 v[42:43], v[42:43], v[162:163]
	v_pk_add_f32 v[44:45], v[44:45], v[164:165]
	v_pk_add_f32 v[38:39], v[38:39], v[166:167]
	v_pk_add_f32 v[40:41], v[40:41], v[168:169]
	v_pk_add_f32 v[34:35], v[34:35], v[186:187]
	v_pk_add_f32 v[36:37], v[36:37], v[188:189]
	v_mul_f32_e32 v233, v46, v46
	v_mul_f32_e32 v250, v42, v42
	v_fmac_f32_e32 v233, v47, v47
	v_fmac_f32_e32 v233, v48, v48
	v_fmac_f32_e32 v233, v49, v49
	v_fmac_f32_e32 v250, v43, v43
	v_fmac_f32_e32 v250, v44, v44
	v_fmac_f32_e32 v250, v45, v45
	v_fmac_f32_e32 v233, v38, v38
	v_fmac_f32_e32 v233, v39, v39
	v_fmac_f32_e32 v233, v40, v40
	v_fmac_f32_e32 v233, v41, v41
	v_fmac_f32_e32 v250, v34, v34
	v_fmac_f32_e32 v250, v35, v35
	v_fmac_f32_e32 v250, v36, v36
	v_fmac_f32_e32 v250, v37, v37
	v_add_f32_e32 v233, v233, v250
	ds_bpermute_b32 v250, v177, v233
	s_waitcnt lgkmcnt(0)
	v_add_f32_e32 v233, v233, v250
	v_mov_b32_e32 v250, v233
	s_nop 1
	v_permlane32_swap_b32_e32 v250, v233
	v_add_f32_e32 v251, v233, v250
	s_and_saveexec_b64 s[62:63], s[42:43]
	global_store_dword v176, v251, s[60:61] sc1
	s_or_b64 exec, exec, s[62:63]
	s_add_u32 s60, s60, 0x400
	s_addc_u32 s61, s61, 0
	s_waitcnt vmcnt(8)
	v_pk_add_f32 v[30:31], v[30:31], v[190:191]
	v_pk_add_f32 v[32:33], v[32:33], v[192:193]
	v_pk_add_f32 v[26:27], v[26:27], v[198:199]
	v_pk_add_f32 v[28:29], v[28:29], v[200:201]
	v_pk_add_f32 v[22:23], v[22:23], v[202:203]
	v_pk_add_f32 v[24:25], v[24:25], v[204:205]
	v_pk_add_f32 v[18:19], v[18:19], v[210:211]
	v_pk_add_f32 v[20:21], v[20:21], v[212:213]
	v_mul_f32_e32 v233, v30, v30
	v_mul_f32_e32 v250, v26, v26
	v_fmac_f32_e32 v233, v31, v31
	v_fmac_f32_e32 v233, v32, v32
	v_fmac_f32_e32 v233, v33, v33
	v_fmac_f32_e32 v250, v27, v27
	v_fmac_f32_e32 v250, v28, v28
	v_fmac_f32_e32 v250, v29, v29
	v_fmac_f32_e32 v233, v22, v22
	v_fmac_f32_e32 v233, v23, v23
	v_fmac_f32_e32 v233, v24, v24
	v_fmac_f32_e32 v233, v25, v25
	v_fmac_f32_e32 v250, v18, v18
	v_fmac_f32_e32 v250, v19, v19
	v_fmac_f32_e32 v250, v20, v20
	v_fmac_f32_e32 v250, v21, v21
	v_add_f32_e32 v233, v233, v250
	ds_bpermute_b32 v250, v177, v233
	s_waitcnt lgkmcnt(0)
	v_add_f32_e32 v233, v233, v250
	v_mov_b32_e32 v250, v233
	s_nop 1
	v_permlane32_swap_b32_e32 v250, v233
	v_add_f32_e32 v251, v233, v250
	s_and_saveexec_b64 s[62:63], s[42:43]
	global_store_dword v176, v251, s[60:61] sc1
	s_or_b64 exec, exec, s[62:63]
	s_add_u32 s60, s60, 0x400
	s_addc_u32 s61, s61, 0
	s_waitcnt vmcnt(4)
	v_pk_add_f32 v[14:15], v[14:15], v[234:235]
	v_pk_add_f32 v[16:17], v[16:17], v[236:237]
	v_pk_add_f32 v[10:11], v[10:11], v[238:239]
	v_pk_add_f32 v[12:13], v[12:13], v[240:241]
	v_pk_add_f32 v[6:7], v[6:7], v[242:243]
	v_pk_add_f32 v[8:9], v[8:9], v[244:245]
	v_pk_add_f32 v[2:3], v[2:3], v[246:247]
	v_pk_add_f32 v[4:5], v[4:5], v[248:249]
	v_mul_f32_e32 v233, v14, v14
	v_mul_f32_e32 v250, v10, v10
	v_fmac_f32_e32 v233, v15, v15
	v_fmac_f32_e32 v233, v16, v16
	v_fmac_f32_e32 v233, v17, v17
	v_fmac_f32_e32 v250, v11, v11
	v_fmac_f32_e32 v250, v12, v12
	v_fmac_f32_e32 v250, v13, v13
	v_fmac_f32_e32 v233, v6, v6
	v_fmac_f32_e32 v233, v7, v7
	v_fmac_f32_e32 v233, v8, v8
	v_fmac_f32_e32 v233, v9, v9
	v_fmac_f32_e32 v250, v2, v2
	v_fmac_f32_e32 v250, v3, v3
	v_fmac_f32_e32 v250, v4, v4
	v_fmac_f32_e32 v250, v5, v5
	v_add_f32_e32 v233, v233, v250
	ds_bpermute_b32 v250, v177, v233
	s_waitcnt lgkmcnt(0)
	v_add_f32_e32 v233, v233, v250
	v_mov_b32_e32 v250, v233
	s_nop 1
	v_permlane32_swap_b32_e32 v250, v233
	v_add_f32_e32 v251, v233, v250
	s_and_saveexec_b64 s[62:63], s[42:43]
	global_store_dword v176, v251, s[60:61] sc1
	s_or_b64 exec, exec, s[62:63]
	v_readlane_b32 s72, v254, 31
	v_readlane_b32 s73, v254, 32
	v_readlane_b32 s76, v254, 38
	v_readlane_b32 s77, v254, 39
	v_readlane_b32 s78, v254, 40
	v_readlane_b32 s79, v254, 41

;     __device__ __forceinline__ void operator()(f32x4 (&acc)[2][2][4][2], const Unit& u, int wr, int wc, int fr, int fq) const {
;     ...
; #pragma unroll
;         for (int ai = 0; ai < 2; ++ai)
; #pragma unroll
;             for (int m = 0; m < 4; ++m) {
;                 const int row = row0 + ai * HALF + m * 16; float sq = 0.f;
; #pragma unroll
;                 for (int i = 0; i < 4; ++i) sq += __hip_atomic_load(part + (size_t)row * 16 + 4 * fq + i, __ATOMIC_RELAXED, __HIP_MEMORY_SCOPE_AGENT);
;                 sq += __shfl_xor(sq, 16); sq += __shfl_xor(sq, 32);
;                 const float rs = rsqrtf(sq * (1.f / 1024.f) + 1e-6f);
.LBB0_1773:
	v_lshl_add_u64 v[170:171], v[136:137], 0, v[190:191]
	s_waitcnt vmcnt(0) lgkmcnt(0)
	s_barrier
	s_waitcnt vmcnt(0) lgkmcnt(0)
	buffer_inv sc1
	v_lshlrev_b32_e32 v170, 12, v184
	v_lshl_add_u32 v170, v195, 2, v170
	v_and_b32_e32 v233, 48, v221
	v_lshl_add_u32 v176, v184, 6, v233
	v_lshlrev_b32_e32 v206, 2, v195
	v_xor_b32_e32 v177, 16, v221
	v_lshlrev_b32_e32 v177, 2, v177
	s_lshl_b32 s65, s32, 14
	s_add_u32 s60, s10, s65
	s_addc_u32 s61, s11, 0
	s_lshl_b32 s65, s51, 10
	s_add_u32 s62, s52, s65
	s_addc_u32 s63, s53, 0
	s_lshl_b32 s65, s32, 20
	s_add_u32 s98, s54, s65
	s_addc_u32 s99, s55, 0
	s_lshl_b32 s65, s51, 10
	s_add_u32 s98, s98, s65
	s_addc_u32 s99, s99, 0
	global_load_dwordx4 v[142:145], v176, s[60:61] sc1
	s_add_u32 s60, s60, 0x400
	s_addc_u32 s61, s61, 0
	global_load_dwordx4 v[146:149], v176, s[60:61] sc1
	s_add_u32 s60, s60, 0x400
	s_addc_u32 s61, s61, 0
	global_load_dwordx4 v[150:153], v176, s[60:61] sc1
	s_add_u32 s60, s60, 0x400
	s_addc_u32 s61, s61, 0
	global_load_dwordx4 v[154:157], v176, s[60:61] sc1
	s_add_u32 s60, s60, 0x1400
	s_addc_u32 s61, s61, 0
	global_load_dwordx4 v[158:161], v176, s[60:61] sc1
	s_add_u32 s60, s60, 0x400
	s_addc_u32 s61, s61, 0
	global_load_dwordx4 v[162:165], v176, s[60:61] sc1
	s_add_u32 s60, s60, 0x400
	s_addc_u32 s61, s61, 0
	global_load_dwordx4 v[166:169], v176, s[60:61] sc1
	s_add_u32 s60, s60, 0x400
	s_addc_u32 s61, s61, 0
	global_load_dwordx4 v[186:189], v176, s[60:61] sc1
	global_load_dwordx4 v[190:193], v206, s[62:63]
	global_load_dwordx4 v[198:201], v206, s[62:63] offset:16
	global_load_dwordx4 v[202:205], v206, s[62:63] offset:512
	global_load_dwordx4 v[246:249], v206, s[62:63] offset:528
	s_waitcnt vmcnt(4)
	v_add_f32_e32 v210, v142, v143
	v_add_f32_e32 v238, v144, v145
	v_add_f32_e32 v211, v146, v147
	v_add_f32_e32 v239, v148, v149
	v_add_f32_e32 v212, v150, v151
	v_add_f32_e32 v240, v152, v153
	v_add_f32_e32 v213, v154, v155
	v_add_f32_e32 v241, v156, v157
	v_add_f32_e32 v234, v158, v159
	v_add_f32_e32 v242, v160, v161
	v_add_f32_e32 v235, v162, v163
	v_add_f32_e32 v243, v164, v165
	v_add_f32_e32 v236, v166, v167
	v_add_f32_e32 v244, v168, v169
	v_add_f32_e32 v237, v186, v187
	v_add_f32_e32 v245, v188, v189
	v_add_f32_e32 v210, v210, v238
	v_add_f32_e32 v211, v211, v239
	v_add_f32_e32 v212, v212, v240
	v_add_f32_e32 v213, v213, v241
	v_add_f32_e32 v234, v234, v242
	v_add_f32_e32 v235, v235, v243
	v_add_f32_e32 v236, v236, v244
	v_add_f32_e32 v237, v237, v245
	ds_bpermute_b32 v238, v177, v210
	ds_bpermute_b32 v239, v177, v211
	ds_bpermute_b32 v240, v177, v212
	ds_bpermute_b32 v241, v177, v213
	ds_bpermute_b32 v242, v177, v234
	ds_bpermute_b32 v243, v177, v235
	ds_bpermute_b32 v244, v177, v236
	ds_bpermute_b32 v245, v177, v237
	s_waitcnt lgkmcnt(0)
	v_add_f32_e32 v210, v210, v238
	v_add_f32_e32 v211, v211, v239
	v_add_f32_e32 v212, v212, v240
	v_add_f32_e32 v213, v213, v241
	v_add_f32_e32 v234, v234, v242
	v_add_f32_e32 v235, v235, v243
	v_add_f32_e32 v236, v236, v244
	v_add_f32_e32 v237, v237, v245
	v_mov_b32_e32 v238, v210
	v_mov_b32_e32 v239, v211
	v_mov_b32_e32 v240, v212
	v_mov_b32_e32 v241, v213
	v_mov_b32_e32 v242, v234
	v_mov_b32_e32 v243, v235
	v_mov_b32_e32 v244, v236
	v_mov_b32_e32 v245, v237
	s_nop 1
	v_permlane32_swap_b32_e32 v238, v210
	v_permlane32_swap_b32_e32 v239, v211
	v_permlane32_swap_b32_e32 v240, v212
	v_permlane32_swap_b32_e32 v241, v213
	v_permlane32_swap_b32_e32 v242, v234
	v_permlane32_swap_b32_e32 v243, v235
	v_permlane32_swap_b32_e32 v244, v236
	v_permlane32_swap_b32_e32 v245, v237
	v_add_f32_e32 v210, v210, v238
	v_add_f32_e32 v211, v211, v239
	v_add_f32_e32 v212, v212, v240
	v_add_f32_e32 v213, v213, v241
	v_add_f32_e32 v234, v234, v242
	v_add_f32_e32 v235, v235, v243
	v_add_f32_e32 v236, v236, v244
	v_add_f32_e32 v237, v237, v245
	s_mov_b32 s65, 0x800000
	v_fmamk_f32 v210, v210, 0x3a800000, v215
	v_cmp_gt_f32_e32 vcc, s65, v210
	v_mul_f32_e32 v238, 0x4b800000, v210
	s_nop 0
	v_cndmask_b32_e32 v210, v210, v238, vcc
	v_rsq_f32_e32 v210, v210
	s_nop 0
	v_mul_f32_e32 v238, 0x45800000, v210
	v_cndmask_b32_e32 v210, v210, v238, vcc
	v_fmamk_f32 v211, v211, 0x3a800000, v215
	v_cmp_gt_f32_e32 vcc, s65, v211
	v_mul_f32_e32 v239, 0x4b800000, v211
	s_nop 0
	v_cndmask_b32_e32 v211, v211, v239, vcc
	v_rsq_f32_e32 v211, v211
	s_nop 0
	v_mul_f32_e32 v239, 0x45800000, v211
	v_cndmask_b32_e32 v211, v211, v239, vcc
	v_fmamk_f32 v212, v212, 0x3a800000, v215
	v_cmp_gt_f32_e32 vcc, s65, v212
	v_mul_f32_e32 v240, 0x4b800000, v212
	s_nop 0
	v_cndmask_b32_e32 v212, v212, v240, vcc
	v_rsq_f32_e32 v212, v212
	s_nop 0
	v_mul_f32_e32 v240, 0x45800000, v212
	v_cndmask_b32_e32 v212, v212, v240, vcc
	v_fmamk_f32 v213, v213, 0x3a800000, v215
	v_cmp_gt_f32_e32 vcc, s65, v213
	v_mul_f32_e32 v241, 0x4b800000, v213
	s_nop 0
	v_cndmask_b32_e32 v213, v213, v241, vcc
	v_rsq_f32_e32 v213, v213
	s_nop 0
	v_mul_f32_e32 v241, 0x45800000, v213
	v_cndmask_b32_e32 v213, v213, v241, vcc
	v_fmamk_f32 v234, v234, 0x3a800000, v215
	v_cmp_gt_f32_e32 vcc, s65, v234
	v_mul_f32_e32 v242, 0x4b800000, v234
	s_nop 0
	v_cndmask_b32_e32 v234, v234, v242, vcc
	v_rsq_f32_e32 v234, v234
	s_nop 0
	v_mul_f32_e32 v242, 0x45800000, v234
	v_cndmask_b32_e32 v234, v234, v242, vcc
	v_fmamk_f32 v235, v235, 0x3a800000, v215
	v_cmp_gt_f32_e32 vcc, s65, v235
	v_mul_f32_e32 v243, 0x4b800000, v235
	s_nop 0
	v_cndmask_b32_e32 v235, v235, v243, vcc
	v_rsq_f32_e32 v235, v235
	s_nop 0
	v_mul_f32_e32 v243, 0x45800000, v235
	v_cndmask_b32_e32 v235, v235, v243, vcc
	v_fmamk_f32 v236, v236, 0x3a800000, v215
	v_cmp_gt_f32_e32 vcc, s65, v236
	v_mul_f32_e32 v244, 0x4b800000, v236
	s_nop 0
	v_cndmask_b32_e32 v236, v236, v244, vcc
	v_rsq_f32_e32 v236, v236
	s_nop 0
	v_mul_f32_e32 v244, 0x45800000, v236
	v_cndmask_b32_e32 v236, v236, v244, vcc
	v_fmamk_f32 v237, v237, 0x3a800000, v215
	v_cmp_gt_f32_e32 vcc, s65, v237
	v_mul_f32_e32 v245, 0x4b800000, v237
	s_nop 0
	v_cndmask_b32_e32 v237, v237, v245, vcc
	v_rsq_f32_e32 v237, v237
	s_nop 0
	v_mul_f32_e32 v245, 0x45800000, v237
	v_cndmask_b32_e32 v237, v237, v245, vcc
	s_waitcnt vmcnt(0)
;     __device__ __forceinline__ void operator()(f32x4 (&acc)[2][2][4][2], const Unit& u, int wr, int wc, int fr, int fq) const {
;     ...
; #pragma unroll
;                 for (int bj = 0; bj < 2; ++bj) { const int col = col0 + bj * HALF; const f32x4 g0 = *(const f32x4*)(gain + col), g1 = *(const f32x4*)(gain + col + 4);
;                     f32x4* op = (f32x4*)(Out + (size_t)row * 1024 + col); op[0] = acc[ai][bj][m][0] * rs * g0; op[1] = acc[ai][bj][m][1] * rs * g1; }
	v_mul_f32_e32 v126, v126, v210
	v_mul_f32_e32 v127, v127, v210
	v_mul_f32_e32 v128, v128, v210
	v_mul_f32_e32 v129, v129, v210
	v_mul_f32_e32 v122, v122, v210
	v_mul_f32_e32 v123, v123, v210
	v_mul_f32_e32 v124, v124, v210
	v_mul_f32_e32 v125, v125, v210
	v_mul_f32_e32 v118, v118, v210
	v_mul_f32_e32 v119, v119, v210
	v_mul_f32_e32 v120, v120, v210
	v_mul_f32_e32 v121, v121, v210
	v_mul_f32_e32 v114, v114, v210
	v_mul_f32_e32 v115, v115, v210
	v_mul_f32_e32 v116, v116, v210
	v_mul_f32_e32 v117, v117, v210
	v_mul_f32_e32 v126, v190, v126
	v_mul_f32_e32 v127, v191, v127
	v_mul_f32_e32 v128, v192, v128
	v_mul_f32_e32 v129, v193, v129
	v_mul_f32_e32 v122, v198, v122
	v_mul_f32_e32 v123, v199, v123
	v_mul_f32_e32 v124, v200, v124
	v_mul_f32_e32 v125, v201, v125
	v_mul_f32_e32 v118, v202, v118
	v_mul_f32_e32 v119, v203, v119
	v_mul_f32_e32 v120, v204, v120
	v_mul_f32_e32 v121, v205, v121
	v_mul_f32_e32 v114, v246, v114
	v_mul_f32_e32 v115, v247, v115
	v_mul_f32_e32 v116, v248, v116
	v_mul_f32_e32 v117, v249, v117
	global_store_dwordx4 v170, v[126:129], s[98:99]
	global_store_dwordx4 v170, v[122:125], s[98:99] offset:16
	global_store_dwordx4 v170, v[118:121], s[98:99] offset:512
	global_store_dwordx4 v170, v[114:117], s[98:99] offset:528
	s_add_u32 s98, s98, 0x10000
	s_addc_u32 s99, s99, 0
	v_mul_f32_e32 v110, v110, v211
	v_mul_f32_e32 v111, v111, v211
	v_mul_f32_e32 v112, v112, v211
	v_mul_f32_e32 v113, v113, v211
	v_mul_f32_e32 v106, v106, v211
	v_mul_f32_e32 v107, v107, v211
	v_mul_f32_e32 v108, v108, v211
	v_mul_f32_e32 v109, v109, v211
	v_mul_f32_e32 v102, v102, v211
	v_mul_f32_e32 v103, v103, v211
	v_mul_f32_e32 v104, v104, v211
	v_mul_f32_e32 v105, v105, v211
	v_mul_f32_e32 v98, v98, v211
	v_mul_f32_e32 v99, v99, v211
	v_mul_f32_e32 v100, v100, v211
	v_mul_f32_e32 v101, v101, v211
	v_mul_f32_e32 v110, v190, v110
	v_mul_f32_e32 v111, v191, v111
	v_mul_f32_e32 v112, v192, v112
	v_mul_f32_e32 v113, v193, v113
	v_mul_f32_e32 v106, v198, v106
	v_mul_f32_e32 v107, v199, v107
	v_mul_f32_e32 v108, v200, v108
	v_mul_f32_e32 v109, v201, v109
	v_mul_f32_e32 v102, v202, v102
	v_mul_f32_e32 v103, v203, v103
	v_mul_f32_e32 v104, v204, v104
	v_mul_f32_e32 v105, v205, v105
	v_mul_f32_e32 v98, v246, v98
	v_mul_f32_e32 v99, v247, v99
	v_mul_f32_e32 v100, v248, v100
	v_mul_f32_e32 v101, v249, v101
	global_store_dwordx4 v170, v[110:113], s[98:99]
	global_store_dwordx4 v170, v[106:109], s[98:99] offset:16
	global_store_dwordx4 v170, v[102:105], s[98:99] offset:512
	global_store_dwordx4 v170, v[98:101], s[98:99] offset:528
	s_add_u32 s98, s98, 0x10000
	s_addc_u32 s99, s99, 0
	v_mul_f32_e32 v94, v94, v212
	v_mul_f32_e32 v95, v95, v212
	v_mul_f32_e32 v96, v96, v212
	v_mul_f32_e32 v97, v97, v212
	v_mul_f32_e32 v90, v90, v212
	v_mul_f32_e32 v91, v91, v212
	v_mul_f32_e32 v92, v92, v212
	v_mul_f32_e32 v93, v93, v212
	v_mul_f32_e32 v86, v86, v212
	v_mul_f32_e32 v87, v87, v212
	v_mul_f32_e32 v88, v88, v212
	v_mul_f32_e32 v89, v89, v212
	v_mul_f32_e32 v82, v82, v212
	v_mul_f32_e32 v83, v83, v212
	v_mul_f32_e32 v84, v84, v212
	v_mul_f32_e32 v85, v85, v212
	v_mul_f32_e32 v94, v190, v94
	v_mul_f32_e32 v95, v191, v95
	v_mul_f32_e32 v96, v192, v96
	v_mul_f32_e32 v97, v193, v97
	v_mul_f32_e32 v90, v198, v90
	v_mul_f32_e32 v91, v199, v91
	v_mul_f32_e32 v92, v200, v92
	v_mul_f32_e32 v93, v201, v93
	v_mul_f32_e32 v86, v202, v86
	v_mul_f32_e32 v87, v203, v87
	v_mul_f32_e32 v88, v204, v88
	v_mul_f32_e32 v89, v205, v89
	v_mul_f32_e32 v82, v246, v82
	v_mul_f32_e32 v83, v247, v83
	v_mul_f32_e32 v84, v248, v84
	v_mul_f32_e32 v85, v249, v85
	global_store_dwordx4 v170, v[94:97], s[98:99]
	global_store_dwordx4 v170, v[90:93], s[98:99] offset:16
	global_store_dwordx4 v170, v[86:89], s[98:99] offset:512
	global_store_dwordx4 v170, v[82:85], s[98:99] offset:528
	s_add_u32 s98, s98, 0x10000
	s_addc_u32 s99, s99, 0
	v_mul_f32_e32 v78, v78, v213
	v_mul_f32_e32 v79, v79, v213
	v_mul_f32_e32 v80, v80, v213
	v_mul_f32_e32 v81, v81, v213
	v_mul_f32_e32 v74, v74, v213
	v_mul_f32_e32 v75, v75, v213
	v_mul_f32_e32 v76, v76, v213
	v_mul_f32_e32 v77, v77, v213
	v_mul_f32_e32 v70, v70, v213
	v_mul_f32_e32 v71, v71, v213
	v_mul_f32_e32 v72, v72, v213
	v_mul_f32_e32 v73, v73, v213
	v_mul_f32_e32 v66, v66, v213
	v_mul_f32_e32 v67, v67, v213
	v_mul_f32_e32 v68, v68, v213
	v_mul_f32_e32 v69, v69, v213
	v_mul_f32_e32 v78, v190, v78
	v_mul_f32_e32 v79, v191, v79
	v_mul_f32_e32 v80, v192, v80
	v_mul_f32_e32 v81, v193, v81
	v_mul_f32_e32 v74, v198, v74
	v_mul_f32_e32 v75, v199, v75
	v_mul_f32_e32 v76, v200, v76
	v_mul_f32_e32 v77, v201, v77
	v_mul_f32_e32 v70, v202, v70
	v_mul_f32_e32 v71, v203, v71
	v_mul_f32_e32 v72, v204, v72
	v_mul_f32_e32 v73, v205, v73
	v_mul_f32_e32 v66, v246, v66
	v_mul_f32_e32 v67, v247, v67
	v_mul_f32_e32 v68, v248, v68
	v_mul_f32_e32 v69, v249, v69
	global_store_dwordx4 v170, v[78:81], s[98:99]
	global_store_dwordx4 v170, v[74:77], s[98:99] offset:16
	global_store_dwordx4 v170, v[70:73], s[98:99] offset:512
	global_store_dwordx4 v170, v[66:69], s[98:99] offset:528
	s_add_u32 s98, s98, 0x50000
	s_addc_u32 s99, s99, 0
; template <class Epi, class Sched, bool ALIGN_EPI = false, bool SP2 = false>
; __device__ __forceinline__ void gemm_phase(PG8_LAS unsigned char* lds, const Gemm g, const Sched& S, const Epi& E) {
;     ...
;         if (!has_next) break;
;     __device__ __forceinline__ void operator()(f32x4 (&acc)[2][2][4][2], const Unit& u, int wr, int wc, int fr, int fq) const {
;     ...
; #pragma unroll
;                 for (int bj = 0; bj < 2; ++bj) { const int col = col0 + bj * HALF; const f32x4 g0 = *(const f32x4*)(gain + col), g1 = *(const f32x4*)(gain + col + 4);
;                     f32x4* op = (f32x4*)(Out + (size_t)row * 1024 + col); op[0] = acc[ai][bj][m][0] * rs * g0; op[1] = acc[ai][bj][m][1] * rs * g1; }
	v_mul_f32_e32 v62, v62, v234
	v_mul_f32_e32 v63, v63, v234
	v_mul_f32_e32 v64, v64, v234
	v_mul_f32_e32 v65, v65, v234
	v_mul_f32_e32 v58, v58, v234
	v_mul_f32_e32 v59, v59, v234
	v_mul_f32_e32 v60, v60, v234
	v_mul_f32_e32 v61, v61, v234
	v_mul_f32_e32 v54, v54, v234
	v_mul_f32_e32 v55, v55, v234
	v_mul_f32_e32 v56, v56, v234
	v_mul_f32_e32 v57, v57, v234
	v_mul_f32_e32 v50, v50, v234
	v_mul_f32_e32 v51, v51, v234
	v_mul_f32_e32 v52, v52, v234
	v_mul_f32_e32 v53, v53, v234
	v_mul_f32_e32 v62, v190, v62
	v_mul_f32_e32 v63, v191, v63
	v_mul_f32_e32 v64, v192, v64
	v_mul_f32_e32 v65, v193, v65
	v_mul_f32_e32 v58, v198, v58
	v_mul_f32_e32 v59, v199, v59
	v_mul_f32_e32 v60, v200, v60
	v_mul_f32_e32 v61, v201, v61
	v_mul_f32_e32 v54, v202, v54
	v_mul_f32_e32 v55, v203, v55
	v_mul_f32_e32 v56, v204, v56
	v_mul_f32_e32 v57, v205, v57
	v_mul_f32_e32 v50, v246, v50
	v_mul_f32_e32 v51, v247, v51
	v_mul_f32_e32 v52, v248, v52
	v_mul_f32_e32 v53, v249, v53
	global_store_dwordx4 v170, v[62:65], s[98:99]
	global_store_dwordx4 v170, v[58:61], s[98:99] offset:16
	global_store_dwordx4 v170, v[54:57], s[98:99] offset:512
	global_store_dwordx4 v170, v[50:53], s[98:99] offset:528
	s_add_u32 s98, s98, 0x10000
	s_addc_u32 s99, s99, 0
	v_mul_f32_e32 v46, v46, v235
	v_mul_f32_e32 v47, v47, v235
	v_mul_f32_e32 v48, v48, v235
	v_mul_f32_e32 v49, v49, v235
	v_mul_f32_e32 v42, v42, v235
	v_mul_f32_e32 v43, v43, v235
	v_mul_f32_e32 v44, v44, v235
	v_mul_f32_e32 v45, v45, v235
	v_mul_f32_e32 v38, v38, v235
	v_mul_f32_e32 v39, v39, v235
	v_mul_f32_e32 v40, v40, v235
	v_mul_f32_e32 v41, v41, v235
	v_mul_f32_e32 v34, v34, v235
	v_mul_f32_e32 v35, v35, v235
	v_mul_f32_e32 v36, v36, v235
	v_mul_f32_e32 v37, v37, v235
	v_mul_f32_e32 v46, v190, v46
	v_mul_f32_e32 v47, v191, v47
	v_mul_f32_e32 v48, v192, v48
	v_mul_f32_e32 v49, v193, v49
	v_mul_f32_e32 v42, v198, v42
	v_mul_f32_e32 v43, v199, v43
	v_mul_f32_e32 v44, v200, v44
	v_mul_f32_e32 v45, v201, v45
	v_mul_f32_e32 v38, v202, v38
	v_mul_f32_e32 v39, v203, v39
	v_mul_f32_e32 v40, v204, v40
	v_mul_f32_e32 v41, v205, v41
	v_mul_f32_e32 v34, v246, v34
	v_mul_f32_e32 v35, v247, v35
	v_mul_f32_e32 v36, v248, v36
	v_mul_f32_e32 v37, v249, v37
	global_store_dwordx4 v170, v[46:49], s[98:99]
	global_store_dwordx4 v170, v[42:45], s[98:99] offset:16
	global_store_dwordx4 v170, v[38:41], s[98:99] offset:512
	global_store_dwordx4 v170, v[34:37], s[98:99] offset:528
	s_add_u32 s98, s98, 0x10000
	s_addc_u32 s99, s99, 0
	v_mul_f32_e32 v30, v30, v236
	v_mul_f32_e32 v31, v31, v236
	v_mul_f32_e32 v32, v32, v236
	v_mul_f32_e32 v33, v33, v236
	v_mul_f32_e32 v26, v26, v236
	v_mul_f32_e32 v27, v27, v236
	v_mul_f32_e32 v28, v28, v236
	v_mul_f32_e32 v29, v29, v236
	v_mul_f32_e32 v22, v22, v236
	v_mul_f32_e32 v23, v23, v236
	v_mul_f32_e32 v24, v24, v236
	v_mul_f32_e32 v25, v25, v236
	v_mul_f32_e32 v18, v18, v236
	v_mul_f32_e32 v19, v19, v236
	v_mul_f32_e32 v20, v20, v236
	v_mul_f32_e32 v21, v21, v236
	v_mul_f32_e32 v30, v190, v30
	v_mul_f32_e32 v31, v191, v31
	v_mul_f32_e32 v32, v192, v32
	v_mul_f32_e32 v33, v193, v33
	v_mul_f32_e32 v26, v198, v26
	v_mul_f32_e32 v27, v199, v27
	v_mul_f32_e32 v28, v200, v28
	v_mul_f32_e32 v29, v201, v29
	v_mul_f32_e32 v22, v202, v22
	v_mul_f32_e32 v23, v203, v23
	v_mul_f32_e32 v24, v204, v24
	v_mul_f32_e32 v25, v205, v25
	v_mul_f32_e32 v18, v246, v18
	v_mul_f32_e32 v19, v247, v19
	v_mul_f32_e32 v20, v248, v20
	v_mul_f32_e32 v21, v249, v21
	global_store_dwordx4 v170, v[30:33], s[98:99]
	global_store_dwordx4 v170, v[26:29], s[98:99] offset:16
	global_store_dwordx4 v170, v[22:25], s[98:99] offset:512
	global_store_dwordx4 v170, v[18:21], s[98:99] offset:528
	s_add_u32 s98, s98, 0x10000
	s_addc_u32 s99, s99, 0
	v_mul_f32_e32 v14, v14, v237
	v_mul_f32_e32 v15, v15, v237
	v_mul_f32_e32 v16, v16, v237
	v_mul_f32_e32 v17, v17, v237
	v_mul_f32_e32 v10, v10, v237
	v_mul_f32_e32 v11, v11, v237
	v_mul_f32_e32 v12, v12, v237
	v_mul_f32_e32 v13, v13, v237
	v_mul_f32_e32 v6, v6, v237
	v_mul_f32_e32 v7, v7, v237
	v_mul_f32_e32 v8, v8, v237
	v_mul_f32_e32 v9, v9, v237
	v_mul_f32_e32 v2, v2, v237
	v_mul_f32_e32 v3, v3, v237
	v_mul_f32_e32 v4, v4, v237
	v_mul_f32_e32 v5, v5, v237
	v_mul_f32_e32 v14, v190, v14
	v_mul_f32_e32 v15, v191, v15
	v_mul_f32_e32 v16, v192, v16
	v_mul_f32_e32 v17, v193, v17
	v_mul_f32_e32 v10, v198, v10
	v_mul_f32_e32 v11, v199, v11
	v_mul_f32_e32 v12, v200, v12
	v_mul_f32_e32 v13, v201, v13
	v_mul_f32_e32 v6, v202, v6
	v_mul_f32_e32 v7, v203, v7
	v_mul_f32_e32 v8, v204, v8
	v_mul_f32_e32 v9, v205, v9
	v_mul_f32_e32 v2, v246, v2
	v_mul_f32_e32 v3, v247, v3
	v_mul_f32_e32 v4, v248, v4
	v_mul_f32_e32 v5, v249, v5
	global_store_dwordx4 v170, v[14:17], s[98:99]
	global_store_dwordx4 v170, v[10:13], s[98:99] offset:16
	global_store_dwordx4 v170, v[6:9], s[98:99] offset:512
	global_store_dwordx4 v170, v[2:5], s[98:99] offset:528
	s_mov_b64 s[16:17], -1
	s_and_b64 vcc, exec, s[46:47]
	s_cbranch_vccnz .LBB0_1727
	v_readlane_b32 s16, v254, 55
	v_readlane_b32 s17, v254, 56
	s_andn2_b64 vcc, exec, s[16:17]
	s_cbranch_vccnz .LBB0_1726
	s_barrier
	s_branch .LBB0_1726
